# scan stage-C loads hoisted + sample-row GEMM units with all 32 loads in flight, strict register pool, 3 instances
# baseline (speedup 1.0000x reference)
.LBB0_1271:
	s_lshr_b32 s10, s9, 3
	s_and_b32 s11, s3, 0xe0
	s_lshl_b32 s12, s10, 20
	s_add_u32 s12, s30, s12
	s_addc_u32 s13, s31, 0
	s_lshl_b32 s14, s11, 12
	s_add_u32 s12, s12, s14
	s_addc_u32 s13, s13, 0
	s_add_u32 s12, s12, s0
	s_addc_u32 s13, s13, s1
	v_lshl_add_u64 v[32:33], s[12:13], 0, v[26:27]
	v_lshl_add_u64 v[76:77], v[32:33], 0, v[28:29]
	v_add_co_u32_e32 v78, vcc, s2, v76
	s_nop 1
	v_addc_co_u32_e32 v79, vcc, 0, v77, vcc
	s_and_b64 vcc, exec, s[6:7]
	global_load_dwordx4 v[100:103], v[76:77], off
	global_load_dwordx4 v[104:107], v[8:9], off
	global_load_dwordx4 v[108:111], v[10:11], off
	global_load_dwordx4 v[112:115], v[8:9], off offset:64
	global_load_dwordx4 v[116:119], v[76:77], off offset:64
	global_load_dwordx4 v[120:123], v[78:79], off
	global_load_dwordx4 v[124:127], v[12:13], off
	global_load_dwordx4 v[128:131], v[78:79], off offset:64
	global_load_dwordx4 v[132:135], v[76:77], off offset:128
	global_load_dwordx4 v[144:147], v[8:9], off offset:128
	global_load_dwordx4 v[148:151], v[14:15], off
	global_load_dwordx4 v[152:155], v[8:9], off offset:192
	global_load_dwordx4 v[156:159], v[76:77], off offset:192
	global_load_dwordx4 v[160:163], v[78:79], off offset:128
	global_load_dwordx4 v[164:167], v[16:17], off
	global_load_dwordx4 v[168:171], v[78:79], off offset:192
	global_load_dwordx4 v[176:179], v[76:77], off offset:256
	global_load_dwordx4 v[180:183], v[8:9], off offset:256
	global_load_dwordx4 v[184:187], v[18:19], off
	global_load_dwordx4 v[188:191], v[8:9], off offset:320
	global_load_dwordx4 v[192:195], v[76:77], off offset:320
	global_load_dwordx4 v[196:199], v[78:79], off offset:256
	global_load_dwordx4 v[200:203], v[20:21], off
	global_load_dwordx4 v[204:207], v[78:79], off offset:320
	global_load_dwordx4 v[208:211], v[76:77], off offset:384
	global_load_dwordx4 v[212:215], v[8:9], off offset:384
	global_load_dwordx4 v[216:219], v[22:23], off
	global_load_dwordx4 v[220:223], v[8:9], off offset:448
	global_load_dwordx4 v[224:227], v[76:77], off offset:448
	global_load_dwordx4 v[228:231], v[78:79], off offset:384
	global_load_dwordx4 v[232:235], v[24:25], off
	global_load_dwordx4 v[236:239], v[78:79], off offset:448
	s_waitcnt vmcnt(30)
	v_mfma_f32_16x16x32_bf16 v[52:55], v[100:103], v[104:107], 0
	s_waitcnt vmcnt(29)
	v_mfma_f32_16x16x32_bf16 v[32:35], v[100:103], v[108:111], 0
	s_waitcnt vmcnt(26)
	v_mfma_f32_16x16x32_bf16 v[36:39], v[120:123], v[104:107], 0
	v_mfma_f32_16x16x32_bf16 v[52:55], v[116:119], v[112:115], v[52:55]
	s_waitcnt vmcnt(25)
	v_mfma_f32_16x16x32_bf16 v[32:35], v[116:119], v[124:127], v[32:35]
	v_mfma_f32_16x16x32_bf16 v[40:43], v[120:123], v[108:111], 0
	s_waitcnt vmcnt(24)
	v_mfma_f32_16x16x32_bf16 v[36:39], v[128:131], v[112:115], v[36:39]
	v_mfma_f32_16x16x32_bf16 v[40:43], v[128:131], v[124:127], v[40:43]
	s_waitcnt vmcnt(22)
	v_mfma_f32_16x16x32_bf16 v[52:55], v[132:135], v[144:147], v[52:55]
	s_waitcnt vmcnt(21)
	v_mfma_f32_16x16x32_bf16 v[32:35], v[132:135], v[148:151], v[32:35]
	s_waitcnt vmcnt(18)
	v_mfma_f32_16x16x32_bf16 v[36:39], v[160:163], v[144:147], v[36:39]
	v_mfma_f32_16x16x32_bf16 v[44:47], v[156:159], v[152:155], v[52:55]
	s_nop 2
	v_mfma_f32_16x16x32_bf16 v[40:43], v[160:163], v[148:151], v[40:43]
	s_waitcnt vmcnt(17)
	v_mfma_f32_16x16x32_bf16 v[32:35], v[156:159], v[164:167], v[32:35]
	s_waitcnt vmcnt(16)
	v_mfma_f32_16x16x32_bf16 v[36:39], v[168:171], v[152:155], v[36:39]
	v_mfma_f32_16x16x32_bf16 v[40:43], v[168:171], v[164:167], v[40:43]
	s_waitcnt vmcnt(14)
	v_mfma_f32_16x16x32_bf16 v[44:47], v[176:179], v[180:183], v[44:47]
	s_waitcnt vmcnt(13)
	v_mfma_f32_16x16x32_bf16 v[32:35], v[176:179], v[184:187], v[32:35]
	s_waitcnt vmcnt(10)
	v_mfma_f32_16x16x32_bf16 v[40:43], v[196:199], v[184:187], v[40:43]
	v_mfma_f32_16x16x32_bf16 v[36:39], v[196:199], v[180:183], v[36:39]
	v_mfma_f32_16x16x32_bf16 v[44:47], v[192:195], v[188:191], v[44:47]
	s_waitcnt vmcnt(9)
	v_mfma_f32_16x16x32_bf16 v[32:35], v[192:195], v[200:203], v[32:35]
	s_waitcnt vmcnt(8)
	v_mfma_f32_16x16x32_bf16 v[36:39], v[204:207], v[188:191], v[36:39]
	v_mfma_f32_16x16x32_bf16 v[40:43], v[204:207], v[200:203], v[40:43]
	s_waitcnt vmcnt(6)
	v_mfma_f32_16x16x32_bf16 v[44:47], v[208:211], v[212:215], v[44:47]
	s_waitcnt vmcnt(5)
	v_mfma_f32_16x16x32_bf16 v[32:35], v[208:211], v[216:219], v[32:35]
	s_barrier
	s_waitcnt vmcnt(2)
	v_mfma_f32_16x16x32_bf16 v[36:39], v[228:231], v[212:215], v[36:39]
	v_mfma_f32_16x16x32_bf16 v[40:43], v[228:231], v[216:219], v[40:43]
	v_mfma_f32_16x16x32_bf16 v[44:47], v[224:227], v[220:223], v[44:47]
	s_waitcnt vmcnt(1)
	v_mfma_f32_16x16x32_bf16 v[32:35], v[224:227], v[232:235], v[32:35]
	s_nop 5
	ds_write_b128 v30, v[44:47]
	s_nop 0
	ds_write_b128 v30, v[32:35] offset:32
	s_waitcnt vmcnt(0)
	v_mfma_f32_16x16x32_bf16 v[36:39], v[236:239], v[220:223], v[36:39]
	v_mfma_f32_16x16x32_bf16 v[32:35], v[236:239], v[232:235], v[40:43]
	s_nop 6
	ds_write_b128 v30, v[36:39] offset:16
	ds_write_b128 v30, v[32:35] offset:48
	s_waitcnt lgkmcnt(0)
	s_barrier
	s_cbranch_vccnz .LBB0_1270
	v_lshl_or_b32 v2, s10, 8, v140
	v_or_b32_e32 v2, s11, v2
	v_lshlrev_b32_e32 v2, 1, v2
	v_lshl_add_u64 v[32:33], v[4:5], 0, v[2:3]
	global_load_dwordx4 v[32:35], v[32:33], off
	ds_read_b128 v[36:39], v31
	ds_read_b128 v[40:43], v31 offset:16
	ds_read_b128 v[44:47], v31 offset:4096
	ds_read_b128 v[48:51], v31 offset:4112
	ds_read_b128 v[52:55], v31 offset:8192
	ds_read_b128 v[56:59], v31 offset:8208
	ds_read_b128 v[60:63], v31 offset:12288
	ds_read_b128 v[64:67], v31 offset:12304
	ds_read_b128 v[68:71], v31 offset:16384
	ds_read_b128 v[72:75], v31 offset:16400
	ds_read_b128 v[76:79], v31 offset:20480
	ds_read_b128 v[80:83], v31 offset:20496
	ds_read_b128 v[84:87], v31 offset:24576
	ds_read_b128 v[88:91], v31 offset:24592
	ds_read_b128 v[92:95], v31 offset:28672
	ds_read_b128 v[96:99], v31 offset:28688
	s_waitcnt lgkmcnt(14)
	v_pk_add_f32 v[38:39], v[38:39], 0 op_sel_hi:[1,0]
	v_pk_add_f32 v[36:37], v[36:37], 0 op_sel_hi:[1,0]
	v_pk_add_f32 v[42:43], v[42:43], 0 op_sel_hi:[1,0]
	v_pk_add_f32 v[40:41], v[40:41], 0 op_sel_hi:[1,0]
	s_waitcnt lgkmcnt(13)
	v_pk_add_f32 v[38:39], v[38:39], v[46:47]
	v_pk_add_f32 v[36:37], v[36:37], v[44:45]
	s_waitcnt lgkmcnt(12)
	v_pk_add_f32 v[42:43], v[42:43], v[50:51]
	v_pk_add_f32 v[40:41], v[40:41], v[48:49]
	s_waitcnt lgkmcnt(11)
	v_pk_add_f32 v[38:39], v[38:39], v[54:55]
	v_pk_add_f32 v[36:37], v[36:37], v[52:53]
	s_waitcnt lgkmcnt(10)
	v_pk_add_f32 v[42:43], v[42:43], v[58:59]
	v_pk_add_f32 v[40:41], v[40:41], v[56:57]
	s_waitcnt lgkmcnt(9)
	v_pk_add_f32 v[38:39], v[38:39], v[62:63]
	v_pk_add_f32 v[36:37], v[36:37], v[60:61]
	s_waitcnt lgkmcnt(8)
	v_pk_add_f32 v[42:43], v[42:43], v[66:67]
	v_pk_add_f32 v[40:41], v[40:41], v[64:65]
	s_waitcnt lgkmcnt(7)
	v_pk_add_f32 v[38:39], v[38:39], v[70:71]
	v_pk_add_f32 v[36:37], v[36:37], v[68:69]
	s_waitcnt lgkmcnt(6)
	v_pk_add_f32 v[42:43], v[42:43], v[74:75]
	v_pk_add_f32 v[40:41], v[40:41], v[72:73]
	s_waitcnt lgkmcnt(5)
	v_pk_add_f32 v[38:39], v[38:39], v[78:79]
	v_pk_add_f32 v[36:37], v[36:37], v[76:77]
	s_waitcnt lgkmcnt(4)
	v_pk_add_f32 v[42:43], v[42:43], v[82:83]
	v_pk_add_f32 v[40:41], v[40:41], v[80:81]
	s_waitcnt lgkmcnt(3)
	v_pk_add_f32 v[38:39], v[38:39], v[86:87]
	v_pk_add_f32 v[36:37], v[36:37], v[84:85]
	s_waitcnt lgkmcnt(2)
	v_pk_add_f32 v[42:43], v[42:43], v[90:91]
	v_pk_add_f32 v[40:41], v[40:41], v[88:89]
	s_waitcnt lgkmcnt(1)
	v_pk_add_f32 v[38:39], v[38:39], v[94:95]
	v_pk_add_f32 v[36:37], v[36:37], v[92:93]
	s_waitcnt lgkmcnt(0)
	v_pk_add_f32 v[42:43], v[42:43], v[98:99]
	v_pk_add_f32 v[40:41], v[40:41], v[96:97]
	s_waitcnt vmcnt(0)
	v_lshlrev_b32_e32 v44, 16, v32
	v_and_b32_e32 v45, 0xffff0000, v32
	v_lshlrev_b32_e32 v32, 16, v33
	v_and_b32_e32 v33, 0xffff0000, v33
	v_lshlrev_b32_e32 v46, 16, v34
	v_and_b32_e32 v47, 0xffff0000, v34
	v_lshlrev_b32_e32 v34, 16, v35
	v_and_b32_e32 v35, 0xffff0000, v35
	v_pk_add_f32 v[36:37], v[36:37], v[44:45]
	v_pk_add_f32 v[38:39], v[38:39], v[32:33]
	v_pk_add_f32 v[40:41], v[40:41], v[46:47]
	v_pk_add_f32 v[42:43], v[42:43], v[34:35]
	v_cvt_pk_bf16_f32 v32, v36, v37
	v_cvt_pk_bf16_f32 v33, v38, v39
	v_cvt_pk_bf16_f32 v34, v40, v41
	v_cvt_pk_bf16_f32 v35, v42, v43
	v_lshl_add_u64 v[36:37], v[6:7], 0, v[2:3]
	global_store_dwordx4 v[36:37], v[32:35], off
	s_branch .LBB0_1270
